# d5_oproj: o_lat blocks prefetched two blocks ahead (two register sets, loop unrolled by two), on v49
# speedup vs baseline: 1.0046x; 1.0036x over previous
.LBB0_1465:
	s_waitcnt vmcnt(0)
	s_add_i32 s3, s3, s84
	s_cmpk_gt_i32 s3, 0xff
	s_cbranch_scc1 .LBB0_1469
.LBB0_1466:
	s_and_b32 s10, s3, 15
	s_lshl_b32 s9, s10, 7
	v_add_u32_e32 v76, s9, v75
	s_waitcnt vmcnt(17)
	v_lshlrev_b64 v[2:3], 10, v[76:77]
	s_waitcnt vmcnt(2)
	v_lshl_add_u64 v[62:63], v[78:79], 0, v[2:3]
	global_load_dwordx4 v[2:5], v[62:63], off
	global_load_dwordx4 v[6:9], v[62:63], off offset:64
	global_load_dwordx4 v[10:13], v[62:63], off offset:128
	global_load_dwordx4 v[14:17], v[62:63], off offset:192
	global_load_dwordx4 v[18:21], v[62:63], off offset:256
	global_load_dwordx4 v[22:25], v[62:63], off offset:320
	global_load_dwordx4 v[26:29], v[62:63], off offset:384
	global_load_dwordx4 v[30:33], v[62:63], off offset:448
	global_load_dwordx4 v[34:37], v[62:63], off offset:512
	global_load_dwordx4 v[38:41], v[62:63], off offset:576
	global_load_dwordx4 v[42:45], v[62:63], off offset:640
	global_load_dwordx4 v[46:49], v[62:63], off offset:704
	global_load_dwordx4 v[50:53], v[62:63], off offset:768
	global_load_dwordx4 v[54:57], v[62:63], off offset:832
	global_load_dwordx4 v[58:61], v[62:63], off offset:896
	s_nop 0
	global_load_dwordx4 v[62:65], v[62:63], off offset:960
	s_ashr_i32 s4, s3, 4
	s_lshl_b32 s8, s4, 6
	s_add_i32 s6, s8, 64
	s_cmp_lg_u32 s4, 15
	s_cselect_b32 s6, s6, 0x401
	s_lshl_b32 s7, s4, 10
	s_waitcnt vmcnt(17)
	v_or_b32_e32 v66, s7, v1
	v_ashrrev_i32_e32 v67, 31, v66
	v_lshlrev_b64 v[66:67], 14, v[66:67]
	v_lshl_add_u64 v[66:67], s[0:1], 0, v[66:67]
	s_lshl_b32 s4, s10, 10
	v_lshl_add_u64 v[66:67], v[66:67], 0, s[4:5]
	v_lshl_add_u64 v[86:87], v[66:67], 0, v[84:85]
	global_load_dwordx4 v[66:69], v[86:87], off
	global_load_dwordx4 v[70:73], v[86:87], off offset:512
	s_mov_b32 s94, 0x40000
	s_mov_b32 s95, 0
	v_lshl_add_u64 v[120:121], v[86:87], 0, s[94:95]
	global_load_dwordx4 v[112:115], v[120:121], off
	global_load_dwordx4 v[116:119], v[120:121], off offset:512
	s_cmp_ge_i32 s8, s6
	s_barrier
	s_cbranch_scc1 .LBB0_1465
	s_waitcnt vmcnt(0)
	s_lshl_b32 s4, s10, 9
	s_lshl_b32 s4, s4, 1
	v_lshl_add_u64 v[86:87], v[80:81], 0, s[4:5]
	s_lshl_b32 s4, s9, 1
	v_lshl_add_u64 v[88:89], v[82:83], 0, s[4:5]
.LBB0_1468:
	s_and_b32 s4, s7, 16
	s_mulk_i32 s4, 0x410
	s_add_i32 s9, s8, 1
	s_add_i32 s4, s4, 0
	v_lshlrev_b32_e32 v76, 1, v74
	s_add_i32 s96, s6, -1
	v_add3_u32 v93, s4, v91, v84
	v_add3_u32 v76, s4, v92, v76
	s_add_i32 s4, s8, 2
	s_min_i32 s4, s4, s96
	s_waitcnt vmcnt(4)
	ds_write_b128 v93, v[66:69]
	s_waitcnt vmcnt(4)
	ds_write_b128 v93, v[70:73] offset:512
	v_lshl_or_b32 v66, s4, 4, v1
	v_ashrrev_i32_e32 v67, 31, v66
	v_lshlrev_b64 v[66:67], 14, v[66:67]
	v_lshl_add_u64 v[94:95], v[86:87], 0, v[66:67]
	global_load_dwordx4 v[66:69], v[94:95], off
	global_load_dwordx4 v[70:73], v[94:95], off offset:512
	s_waitcnt lgkmcnt(0)
	s_barrier
	ds_read_b128 v[94:97], v76
	ds_read_b128 v[98:101], v76 offset:64
	ds_read_b128 v[102:105], v76 offset:128
	ds_read_b128 v[106:109], v76 offset:192
	s_waitcnt lgkmcnt(3)
	v_mfma_f32_16x16x32_bf16 v[94:97], v[2:5], v[94:97], 0
	v_add_u32_e32 v110, s7, v90
	v_ashrrev_i32_e32 v111, 31, v110
	s_add_i32 s7, s7, 16
	s_waitcnt lgkmcnt(2)
	v_mfma_f32_16x16x32_bf16 v[98:101], v[6:9], v[98:101], 0
	s_mov_b32 s8, s9
	s_cmp_ge_i32 s9, s6
	s_waitcnt lgkmcnt(1)
	v_mfma_f32_16x16x32_bf16 v[94:97], v[10:13], v[102:105], v[94:97]
	s_waitcnt lgkmcnt(0)
	v_mfma_f32_16x16x32_bf16 v[98:101], v[14:17], v[106:109], v[98:101]
	ds_read_b128 v[102:105], v76 offset:256
	ds_read_b128 v[106:109], v76 offset:320
	s_waitcnt lgkmcnt(1)
	v_mfma_f32_16x16x32_bf16 v[94:97], v[18:21], v[102:105], v[94:97]
	s_waitcnt lgkmcnt(0)
	v_mfma_f32_16x16x32_bf16 v[98:101], v[22:25], v[106:109], v[98:101]
	ds_read_b128 v[102:105], v76 offset:384
	ds_read_b128 v[106:109], v76 offset:448
	s_waitcnt lgkmcnt(1)
	v_mfma_f32_16x16x32_bf16 v[94:97], v[26:29], v[102:105], v[94:97]
	s_waitcnt lgkmcnt(0)
	v_mfma_f32_16x16x32_bf16 v[98:101], v[30:33], v[106:109], v[98:101]
	ds_read_b128 v[102:105], v76 offset:512
	ds_read_b128 v[106:109], v76 offset:576
	s_waitcnt lgkmcnt(1)
	v_mfma_f32_16x16x32_bf16 v[94:97], v[34:37], v[102:105], v[94:97]
	s_waitcnt lgkmcnt(0)
	v_mfma_f32_16x16x32_bf16 v[98:101], v[38:41], v[106:109], v[98:101]
	ds_read_b128 v[102:105], v76 offset:640
	ds_read_b128 v[106:109], v76 offset:704
	s_waitcnt lgkmcnt(1)
	v_mfma_f32_16x16x32_bf16 v[94:97], v[42:45], v[102:105], v[94:97]
	s_waitcnt lgkmcnt(0)
	v_mfma_f32_16x16x32_bf16 v[98:101], v[46:49], v[106:109], v[98:101]
	ds_read_b128 v[102:105], v76 offset:768
	ds_read_b128 v[106:109], v76 offset:832
	s_waitcnt lgkmcnt(1)
	v_mfma_f32_16x16x32_bf16 v[94:97], v[50:53], v[102:105], v[94:97]
	v_lshlrev_b64 v[102:103], 12, v[110:111]
	v_lshl_add_u64 v[110:111], v[88:89], 0, v[102:103]
	s_waitcnt lgkmcnt(0)
	v_mfma_f32_16x16x32_bf16 v[98:101], v[54:57], v[106:109], v[98:101]
	ds_read_b128 v[102:105], v76 offset:896
	ds_read_b128 v[106:109], v76 offset:960
	s_waitcnt lgkmcnt(1)
	v_mfma_f32_16x16x32_bf16 v[94:97], v[58:61], v[102:105], v[94:97]
	s_waitcnt lgkmcnt(0)
	v_mfma_f32_16x16x32_bf16 v[98:101], v[62:65], v[106:109], v[98:101]
	s_nop 7
	v_pk_add_f32 v[96:97], v[96:97], v[100:101]
	v_pk_add_f32 v[94:95], v[94:95], v[98:99]
	s_nop 0
	v_cvt_pk_bf16_f32 v94, v94, v95
	v_cvt_pk_bf16_f32 v95, v96, v97
	global_store_dwordx2 v[110:111], v[94:95], off
	s_cbranch_scc1 .LBB0_1465
.Lop_b:
	s_and_b32 s4, s7, 16
	s_mulk_i32 s4, 0x410
	s_add_i32 s9, s8, 1
	s_add_i32 s4, s4, 0
	v_lshlrev_b32_e32 v76, 1, v74
	s_add_i32 s96, s6, -1
	v_add3_u32 v93, s4, v91, v84
	v_add3_u32 v76, s4, v92, v76
	s_add_i32 s4, s8, 2
	s_min_i32 s4, s4, s96
	s_waitcnt vmcnt(4)
	ds_write_b128 v93, v[112:115]
	s_waitcnt vmcnt(4)
	ds_write_b128 v93, v[116:119] offset:512
	v_lshl_or_b32 v112, s4, 4, v1
	v_ashrrev_i32_e32 v113, 31, v112
	v_lshlrev_b64 v[112:113], 14, v[112:113]
	v_lshl_add_u64 v[94:95], v[86:87], 0, v[112:113]
	global_load_dwordx4 v[112:115], v[94:95], off
	global_load_dwordx4 v[116:119], v[94:95], off offset:512
	s_waitcnt lgkmcnt(0)
	s_barrier
	ds_read_b128 v[94:97], v76
	ds_read_b128 v[98:101], v76 offset:64
	ds_read_b128 v[102:105], v76 offset:128
	ds_read_b128 v[106:109], v76 offset:192
	s_waitcnt lgkmcnt(3)
	v_mfma_f32_16x16x32_bf16 v[94:97], v[2:5], v[94:97], 0
	v_add_u32_e32 v110, s7, v90
	v_ashrrev_i32_e32 v111, 31, v110
	s_add_i32 s7, s7, 16
	s_waitcnt lgkmcnt(2)
	v_mfma_f32_16x16x32_bf16 v[98:101], v[6:9], v[98:101], 0
	s_mov_b32 s8, s9
	s_cmp_ge_i32 s9, s6
	s_waitcnt lgkmcnt(1)
	v_mfma_f32_16x16x32_bf16 v[94:97], v[10:13], v[102:105], v[94:97]
	s_waitcnt lgkmcnt(0)
	v_mfma_f32_16x16x32_bf16 v[98:101], v[14:17], v[106:109], v[98:101]
	ds_read_b128 v[102:105], v76 offset:256
	ds_read_b128 v[106:109], v76 offset:320
	s_waitcnt lgkmcnt(1)
	v_mfma_f32_16x16x32_bf16 v[94:97], v[18:21], v[102:105], v[94:97]
	s_waitcnt lgkmcnt(0)
	v_mfma_f32_16x16x32_bf16 v[98:101], v[22:25], v[106:109], v[98:101]
	ds_read_b128 v[102:105], v76 offset:384
	ds_read_b128 v[106:109], v76 offset:448
	s_waitcnt lgkmcnt(1)
	v_mfma_f32_16x16x32_bf16 v[94:97], v[26:29], v[102:105], v[94:97]
	s_waitcnt lgkmcnt(0)
	v_mfma_f32_16x16x32_bf16 v[98:101], v[30:33], v[106:109], v[98:101]
	ds_read_b128 v[102:105], v76 offset:512
	ds_read_b128 v[106:109], v76 offset:576
	s_waitcnt lgkmcnt(1)
	v_mfma_f32_16x16x32_bf16 v[94:97], v[34:37], v[102:105], v[94:97]
	s_waitcnt lgkmcnt(0)
	v_mfma_f32_16x16x32_bf16 v[98:101], v[38:41], v[106:109], v[98:101]
	ds_read_b128 v[102:105], v76 offset:640
	ds_read_b128 v[106:109], v76 offset:704
	s_waitcnt lgkmcnt(1)
	v_mfma_f32_16x16x32_bf16 v[94:97], v[42:45], v[102:105], v[94:97]
	s_waitcnt lgkmcnt(0)
	v_mfma_f32_16x16x32_bf16 v[98:101], v[46:49], v[106:109], v[98:101]
	ds_read_b128 v[102:105], v76 offset:768
	ds_read_b128 v[106:109], v76 offset:832
	s_waitcnt lgkmcnt(1)
	v_mfma_f32_16x16x32_bf16 v[94:97], v[50:53], v[102:105], v[94:97]
	v_lshlrev_b64 v[102:103], 12, v[110:111]
	v_lshl_add_u64 v[110:111], v[88:89], 0, v[102:103]
	s_waitcnt lgkmcnt(0)
	v_mfma_f32_16x16x32_bf16 v[98:101], v[54:57], v[106:109], v[98:101]
	ds_read_b128 v[102:105], v76 offset:896
	ds_read_b128 v[106:109], v76 offset:960
	s_waitcnt lgkmcnt(1)
	v_mfma_f32_16x16x32_bf16 v[94:97], v[58:61], v[102:105], v[94:97]
	s_waitcnt lgkmcnt(0)
	v_mfma_f32_16x16x32_bf16 v[98:101], v[62:65], v[106:109], v[98:101]
	s_nop 7
	v_pk_add_f32 v[96:97], v[96:97], v[100:101]
	v_pk_add_f32 v[94:95], v[94:95], v[98:99]
	s_nop 0
	v_cvt_pk_bf16_f32 v94, v94, v95
	v_cvt_pk_bf16_f32 v95, v96, v97
	global_store_dwordx2 v[110:111], v[94:95], off
	s_cbranch_scc0 .LBB0_1468
	s_branch .LBB0_1465
